# adds: tile-fetch role split - only the trailing wave group (waves 4-7) issues the LDS-DMA loads, each fetching its own eighth and its partner wave's (w-4) eighth; the leading group's step carries no i
# speedup vs baseline: 1.0040x; 1.0040x over previous
.LBB0_148:
	s_add_i32 s36, s57, -2
	s_and_b32 s74, s36, 1
	s_lshl_b32 s36, s74, 14
	s_lshl_b32 s42, s74, 13
	s_add_i32 s42, s42, 0x14000
	v_add3_u32 v210, s36, v222, v221
	v_add3_u32 v211, s36, v223, v221
	v_add3_u32 v212, s36, v224, v221
	v_add3_u32 v213, s36, v225, v221
	ds_read_b128 v[240:243], v210 offset:49152
	ds_read_b128 v[244:247], v211 offset:49152
	ds_read_b128 v[248:251], v212 offset:49152
	ds_read_b128 v[236:239], v213 offset:49152
	ds_read_b128 v[64:67], v210 offset:49280
	ds_read_b128 v[68:71], v211 offset:49280
	ds_read_b128 v[72:75], v212 offset:49280
	ds_read_b128 v[76:79], v213 offset:49280
	s_add_i32 s37, s57, -1
	s_cmp_ge_u32 s37, s33
	s_cbranch_scc1 .Lkvdma_skip
	s_and_b64 vcc, exec, s[80:81]
	s_cbranch_vccz .Lkvdma_skip
	s_and_b32 s37, s37, 1
	s_add_i32 s43, s70, 1
	s_cmp_lg_u32 s70, 2
	s_cselect_b32 s43, s43, 0
	v_readlane_b32 s74, v254, 50
	s_lshl_b32 s75, s43, 14
	s_lshl_b32 s74, s74, 11
	s_add_i32 s75, s75, s74
	s_mov_b32 vcc_lo, 0xfffe8000
	s_mov_b32 vcc_hi, -1
	v_lshl_add_u64 v[154:155], v[146:147], 0, vcc
	s_mov_b32 m0, s75
	s_nop 0
	global_load_lds_dwordx4 v[146:147], off
	s_add_i32 m0, s75, 0x380
	s_nop 0
	global_load_lds_dwordx4 v[146:147], off offset:128
	s_add_i32 m0, s75, 0xffffe000
	s_nop 0
	global_load_lds_dwordx4 v[154:155], off
	s_add_i32 m0, s75, 0xffffe380
	s_nop 0
	global_load_lds_dwordx4 v[154:155], off offset:128
	s_lshl_b32 s75, s37, 14
	s_add_i32 s75, s75, s74
	v_lshl_add_u64 v[154:155], v[148:149], 0, vcc
	s_add_i32 m0, s75, 0xc000
	s_nop 0
	global_load_lds_dwordx4 v[148:149], off
	s_add_i32 m0, s75, 0xc400
	s_nop 0
	global_load_lds_dwordx4 v[150:151], off
	s_add_i32 m0, s75, 0xa000
	s_nop 0
	global_load_lds_dwordx4 v[154:155], off
	v_lshl_add_u64 v[154:155], v[150:151], 0, vcc
	s_add_i32 m0, s75, 0xa400
	s_nop 0
	global_load_lds_dwordx4 v[154:155], off
	s_lshl_b32 s75, s37, 13
	s_lshr_b32 s74, s74, 1
	s_add_i32 s75, s75, s74
	s_mov_b32 vcc_lo, 0xfffff000
	v_lshl_add_u64 v[154:155], v[152:153], 0, vcc
	s_add_i32 m0, s75, 0x14000
	s_nop 0
	global_load_lds_dwordx4 v[152:153], off
	s_add_i32 m0, s75, 0x13000
	s_nop 0
	global_load_lds_dwordx4 v[154:155], off
	s_mul_i32 s74, s100, 24
	s_mov_b32 s75, s101
	v_lshl_add_u64 v[146:147], v[146:147], 0, s[74:75]
	v_lshl_add_u64 v[148:149], v[148:149], 0, s[74:75]
	v_lshl_add_u64 v[150:151], v[150:151], 0, s[74:75]
	v_lshl_add_u64 v[152:153], v[152:153], 0, s[100:101]
